# baseline (speedup 1.0000x reference)
; template <int MODE> __device__ __forceinline__ void diff_attn_item(const bf16* __restrict__ Qb, const bf16* __restrict__ Kh, const bf16* __restrict__ Vh, ...
;     ...
;   if (map == 0) {
;     float ss = 0;
; #pragma unroll
;     for (int d0 = 0; d0 < 4; ++d0)
; #pragma unroll
;       for (int r = 0; r < 16; ++r) { float v = o[d0][r] * rl - E[((rb * 4 + d0) * 16 + r) * 64 + lane]; o[d0][r] = v; ss += v * v; }
;     ss += __shfl_xor(ss, 32);
;     const float rstd = rsqrtf(ss * (1.f / 128.f) + EPS) * oscale;
.LBB0_944:
	s_or_b64 exec, exec, s[8:9]
	s_movk_i32 s7, 0x100
	v_cmp_gt_u32_e32 vcc, s7, v163
	s_waitcnt lgkmcnt(0)
	s_barrier
	s_and_saveexec_b64 s[8:9], vcc
	s_cbranch_execz .LBB0_787
	global_load_dwordx4 v[106:109], v16, s[4:5]
	global_load_dwordx4 v[110:113], v16, s[4:5] offset:32
	global_load_dwordx4 v[114:117], v16, s[4:5] offset:64
	global_load_dwordx4 v[118:121], v16, s[4:5] offset:96
	global_load_dwordx4 v[122:125], v16, s[4:5] offset:128
	global_load_dwordx4 v[126:129], v16, s[4:5] offset:160
	global_load_dwordx4 v[130:133], v16, s[4:5] offset:192
	global_load_dwordx4 v[134:137], v16, s[4:5] offset:224
	global_load_dwordx4 v[138:141], v16, s[4:5] offset:256
	global_load_dwordx4 v[142:145], v16, s[4:5] offset:288
	global_load_dwordx4 v[146:149], v16, s[4:5] offset:320
	global_load_dwordx4 v[150:153], v16, s[4:5] offset:352
	global_load_dwordx4 v[154:157], v16, s[4:5] offset:384
	global_load_dwordx4 v[158:161], v16, s[4:5] offset:416
	global_load_dwordx4 v[200:203], v16, s[4:5] offset:448
	global_load_dwordx4 v[204:207], v16, s[4:5] offset:480
	v_lshlrev_b32_e32 v93, 8, v163
	v_lshl_add_u32 v92, v198, 2, 0
	v_and_b32_e32 v84, 0xc000, v93
	v_add_u32_e32 v94, v92, v84
	ds_read2st64_b32 v[84:85], v94 offset1:1
	ds_read2st64_b32 v[86:87], v94 offset0:2 offset1:3
	ds_read2st64_b32 v[88:89], v94 offset0:4 offset1:5
	ds_read2st64_b32 v[90:91], v94 offset0:6 offset1:7
	s_mov_b32 s7, 0x800000
	s_waitcnt lgkmcnt(3)
	v_fma_f32 v84, v66, v82, -v84
	v_fma_f32 v85, v67, v82, -v85
	s_waitcnt lgkmcnt(2)
	v_fma_f32 v86, v68, v82, -v86
	v_fma_f32 v87, v69, v82, -v87
	s_waitcnt lgkmcnt(1)
	v_fma_f32 v88, v70, v82, -v88
	v_fma_f32 v89, v71, v82, -v89
	s_waitcnt lgkmcnt(0)
	v_fma_f32 v90, v72, v82, -v90
	v_fma_f32 v91, v73, v82, -v91
	ds_read2st64_b32 v[66:67], v94 offset0:8 offset1:9
	ds_read2st64_b32 v[68:69], v94 offset0:10 offset1:11
	ds_read2st64_b32 v[70:71], v94 offset0:12 offset1:13
	ds_read2st64_b32 v[72:73], v94 offset0:14 offset1:15
	v_mul_f32_e32 v95, v85, v85
	v_fmac_f32_e32 v95, v84, v84
	s_waitcnt lgkmcnt(2)
	v_fma_f32 v76, v76, v82, -v68
	v_fma_f32 v74, v74, v82, -v66
	v_fma_f32 v75, v75, v82, -v67
	v_fma_f32 v77, v77, v82, -v69
	s_waitcnt lgkmcnt(1)
	v_fma_f32 v78, v78, v82, -v70
	v_fma_f32 v79, v79, v82, -v71
	s_waitcnt lgkmcnt(0)
	v_fma_f32 v80, v80, v82, -v72
	v_fma_f32 v81, v81, v82, -v73
	ds_read2st64_b32 v[66:67], v94 offset0:16 offset1:17
	ds_read2st64_b32 v[68:69], v94 offset0:18 offset1:19
	ds_read2st64_b32 v[70:71], v94 offset0:20 offset1:21
	ds_read2st64_b32 v[72:73], v94 offset0:22 offset1:23
	v_fmac_f32_e32 v95, v86, v86
	v_fmac_f32_e32 v95, v87, v87
	s_waitcnt lgkmcnt(2)
	v_fma_f32 v68, v52, v82, -v68
	v_fma_f32 v66, v50, v82, -v66
	v_fma_f32 v67, v51, v82, -v67
	v_fma_f32 v69, v53, v82, -v69
	s_waitcnt lgkmcnt(1)
	v_fma_f32 v70, v54, v82, -v70
	v_fma_f32 v71, v55, v82, -v71
	s_waitcnt lgkmcnt(0)
	v_fma_f32 v72, v56, v82, -v72
	v_fma_f32 v73, v57, v82, -v73
	ds_read2st64_b32 v[50:51], v94 offset0:24 offset1:25
	ds_read2st64_b32 v[52:53], v94 offset0:26 offset1:27
	ds_read2st64_b32 v[54:55], v94 offset0:28 offset1:29
	ds_read2st64_b32 v[56:57], v94 offset0:30 offset1:31
	v_fmac_f32_e32 v95, v88, v88
	v_fmac_f32_e32 v95, v89, v89
	s_waitcnt lgkmcnt(2)
	v_fma_f32 v60, v60, v82, -v52
	v_fma_f32 v58, v58, v82, -v50
	v_fma_f32 v59, v59, v82, -v51
	v_fma_f32 v61, v61, v82, -v53
	s_waitcnt lgkmcnt(1)
	v_fma_f32 v62, v62, v82, -v54
	v_fma_f32 v63, v63, v82, -v55
	s_waitcnt lgkmcnt(0)
	v_fma_f32 v64, v64, v82, -v56
	v_fma_f32 v65, v65, v82, -v57
	ds_read2st64_b32 v[50:51], v94 offset0:32 offset1:33
	ds_read2st64_b32 v[52:53], v94 offset0:34 offset1:35
	ds_read2st64_b32 v[54:55], v94 offset0:36 offset1:37
	ds_read2st64_b32 v[56:57], v94 offset0:38 offset1:39
	v_fmac_f32_e32 v95, v90, v90
	v_fmac_f32_e32 v95, v91, v91
	v_fmac_f32_e32 v95, v74, v74
	v_fmac_f32_e32 v95, v75, v75
	s_waitcnt lgkmcnt(2)
	v_fma_f32 v98, v36, v82, -v52
	v_fma_f32 v99, v37, v82, -v53
	s_waitcnt lgkmcnt(1)
	v_fma_f32 v54, v38, v82, -v54
	v_fma_f32 v55, v39, v82, -v55
	v_fmac_f32_e32 v95, v76, v76
	v_fmac_f32_e32 v95, v77, v77
	v_fmac_f32_e32 v95, v78, v78
	v_fmac_f32_e32 v95, v79, v79
	v_fmac_f32_e32 v95, v80, v80
	v_fmac_f32_e32 v95, v81, v81
	v_fmac_f32_e32 v95, v66, v66
	v_fmac_f32_e32 v95, v67, v67
	v_fmac_f32_e32 v95, v68, v68
	v_fmac_f32_e32 v95, v69, v69
	v_fmac_f32_e32 v95, v70, v70
	v_fmac_f32_e32 v95, v71, v71
	v_fmac_f32_e32 v95, v72, v72
	v_fmac_f32_e32 v95, v73, v73
	v_fmac_f32_e32 v95, v58, v58
	v_fmac_f32_e32 v95, v59, v59
	v_fmac_f32_e32 v95, v60, v60
	v_fmac_f32_e32 v95, v61, v61
	v_fmac_f32_e32 v95, v62, v62
	v_fmac_f32_e32 v95, v63, v63
	v_fmac_f32_e32 v95, v64, v64
	v_fmac_f32_e32 v95, v65, v65
	v_fma_f32 v96, v34, v82, -v50
	v_fmac_f32_e32 v95, v96, v96
	v_fma_f32 v97, v35, v82, -v51
	v_fmac_f32_e32 v95, v97, v97
	v_fmac_f32_e32 v95, v98, v98
	ds_read2st64_b32 v[34:35], v94 offset0:40 offset1:41
	v_fmac_f32_e32 v95, v99, v99
	v_fmac_f32_e32 v95, v54, v54
	v_fmac_f32_e32 v95, v55, v55
	s_waitcnt lgkmcnt(1)
	v_fma_f32 v56, v40, v82, -v56
	v_fmac_f32_e32 v95, v56, v56
	v_fma_f32 v57, v41, v82, -v57
	ds_read2st64_b32 v[40:41], v94 offset0:42 offset1:43
	ds_read2st64_b32 v[50:51], v94 offset0:44 offset1:45
	ds_read2st64_b32 v[52:53], v94 offset0:46 offset1:47
	v_fmac_f32_e32 v95, v57, v57
	s_waitcnt lgkmcnt(3)
	v_fma_f32 v100, v42, v82, -v34
	v_fmac_f32_e32 v95, v100, v100
	v_fma_f32 v101, v43, v82, -v35
	v_fmac_f32_e32 v95, v101, v101
	s_waitcnt lgkmcnt(2)
	v_fma_f32 v102, v44, v82, -v40
	v_fmac_f32_e32 v95, v102, v102
	v_fma_f32 v103, v45, v82, -v41
	ds_read2st64_b32 v[34:35], v94 offset0:48 offset1:49
	v_fmac_f32_e32 v95, v103, v103
	s_waitcnt lgkmcnt(2)
; __device__ __forceinline__ u32x2 pack4(float a, float b, float c, float d) { u32x2 r = {cvtpk(a, b), cvtpk(c, d)}; return r; }
; template <int MODE> __device__ __forceinline__ void diff_attn_item(const bf16* __restrict__ Qb, const bf16* __restrict__ Kh, const bf16* __restrict__ Vh, ...
;     ...
;       for (int r = 0; r < 16; ++r) { float v = o[d0][r] * rl - E[((rb * 4 + d0) * 16 + r) * 64 + lane]; o[d0][r] = v; ss += v * v; }
;     ss += __shfl_xor(ss, 32);
;     const float rstd = rsqrtf(ss * (1.f / 128.f) + EPS) * oscale;
;     bf16* orow = outb + (size_t)(rb * 32 + r32) * 1024;
; #pragma unroll
;     for (int d0 = 0; d0 < 4; ++d0)
; #pragma unroll
;       for (int ip = 0; ip < 2; ++ip) {
;         u32x2 pk[2];
; #pragma unroll
;         for (int e = 0; e < 2; ++e) {
;           const int i = ip * 2 + e, dim = d0 * 32 + i * 8;
;           float4 g4 = *reinterpret_cast<const float4*>(sub_g + dim + hi * 4);
;           pk[e] = pack4(o[d0][4 * i] * rstd * g4.x, o[d0][4 * i + 1] * rstd * g4.y, o[d0][4 * i + 2] * rstd * g4.z, o[d0][4 * i + 3] * rstd * g4.w);
;         }
;         *reinterpret_cast<u32x4*>(orow + d0 * 32 + (ip * 2 + hi) * 8) = widen_pair(pk[0], pk[1]);
	v_fma_f32 v46, v46, v82, -v50
	v_fmac_f32_e32 v95, v46, v46
	v_fma_f32 v47, v47, v82, -v51
	v_fmac_f32_e32 v95, v47, v47
	s_waitcnt lgkmcnt(1)
	v_fma_f32 v48, v48, v82, -v52
	v_fmac_f32_e32 v95, v48, v48
	v_fma_f32 v49, v49, v82, -v53
	ds_read2st64_b32 v[40:41], v94 offset0:50 offset1:51
	ds_read2st64_b32 v[42:43], v94 offset0:52 offset1:53
	ds_read2st64_b32 v[44:45], v94 offset0:54 offset1:55
	v_fmac_f32_e32 v95, v49, v49
	s_waitcnt lgkmcnt(3)
	v_fma_f32 v50, v18, v82, -v34
	v_fmac_f32_e32 v95, v50, v50
	v_fma_f32 v51, v19, v82, -v35
	v_fmac_f32_e32 v95, v51, v51
	s_waitcnt lgkmcnt(2)
	v_fma_f32 v52, v20, v82, -v40
	v_fmac_f32_e32 v95, v52, v52
	v_fma_f32 v53, v21, v82, -v41
	v_fmac_f32_e32 v95, v53, v53
	s_waitcnt lgkmcnt(1)
	v_fma_f32 v104, v22, v82, -v42
	ds_read2st64_b32 v[20:21], v94 offset0:56 offset1:57
	v_fmac_f32_e32 v95, v104, v104
	v_fma_f32 v105, v23, v82, -v43
	s_waitcnt lgkmcnt(1)
	v_pk_fma_f32 v[34:35], v[24:25], v[82:83], v[44:45] op_sel_hi:[1,0,1] neg_lo:[0,0,1] neg_hi:[0,0,1]
	v_fmac_f32_e32 v95, v105, v105
	v_pk_mul_f32 v[18:19], v[34:35], v[34:35]
	s_waitcnt lgkmcnt(0)
	v_pk_fma_f32 v[22:23], v[26:27], v[82:83], v[20:21] op_sel_hi:[1,0,1] neg_lo:[0,0,1] neg_hi:[0,0,1]
	v_add_f32_e32 v18, v95, v18
	v_add_f32_e32 v24, v18, v19
	ds_read2st64_b32 v[18:19], v94 offset0:58 offset1:59
	ds_read2st64_b32 v[40:41], v94 offset0:60 offset1:61
	ds_read_b32 v42, v94 offset:15872
	v_pk_mul_f32 v[20:21], v[22:23], v[22:23]
	v_readlane_b32 s12, v255, 22
	v_add_f32_e32 v20, v24, v20
	s_waitcnt lgkmcnt(2)
	v_pk_fma_f32 v[24:25], v[28:29], v[82:83], v[18:19] op_sel_hi:[1,0,1] neg_lo:[0,0,1] neg_hi:[0,0,1]
	v_add_f32_e32 v20, v20, v21
	v_pk_mul_f32 v[18:19], v[24:25], v[24:25]
	v_readlane_b32 s13, v255, 23
	v_add_f32_e32 v18, v20, v18
	v_add_f32_e32 v26, v18, v19
	v_or_b32_e32 v18, 0x3f00, v93
	v_add_u32_e32 v18, v92, v18
	ds_read_b32 v43, v18
	s_waitcnt lgkmcnt(2)
	v_pk_fma_f32 v[18:19], v[30:31], v[82:83], v[40:41] op_sel_hi:[1,0,1] neg_lo:[0,0,1] neg_hi:[0,0,1]
	s_mov_b32 s10, 0x3100000
	v_pk_mul_f32 v[20:21], v[18:19], v[18:19]
	s_nop 0
	v_add_f32_e32 v20, v26, v20
	v_add_f32_e32 v28, v20, v21
	s_waitcnt lgkmcnt(0)
	v_pk_fma_f32 v[20:21], v[32:33], v[82:83], v[42:43] op_sel_hi:[1,0,1] neg_lo:[0,0,1] neg_hi:[0,0,1]
	s_nop 0
	v_pk_mul_f32 v[26:27], v[20:21], v[20:21]
	s_nop 0
	v_add_f32_e32 v26, v28, v26
	v_add_f32_e32 v26, v26, v27
	ds_bpermute_b32 v27, v83, v26
	s_waitcnt lgkmcnt(0)
	v_add_f32_e32 v26, v26, v27
	v_fmamk_f32 v26, v26, 0x3c000000, v195
	v_mul_f32_e32 v27, 0x4b800000, v26
	v_cmp_gt_f32_e32 vcc, s7, v26
	s_ashr_i32 s7, s6, 31
	s_lshl_b64 s[6:7], s[6:7], 11
	v_cndmask_b32_e32 v26, v26, v27, vcc
	v_rsq_f32_e32 v26, v26
	s_add_u32 s6, s12, s6
	s_addc_u32 s7, s13, s7
	s_lshl_b32 s2, s2, 8
	v_mul_f32_e32 v27, 0x45800000, v26
	v_cndmask_b32_e32 v26, v26, v27, vcc
	v_mul_f32_e32 v40, 0x3f4ccccd, v26
	v_mul_f32_e32 v26, v84, v40
	v_mul_f32_e32 v27, v85, v40
	v_mul_f32_e32 v28, v86, v40
	v_mul_f32_e32 v29, v87, v40
	s_waitcnt vmcnt(0)
	v_mov_b32_e32 v36, v106
	v_mov_b32_e32 v37, v107
	v_mov_b32_e32 v38, v108
	v_mov_b32_e32 v39, v109
	v_mul_f32_e32 v26, v36, v26
	v_mul_f32_e32 v27, v37, v27
	v_mul_f32_e32 v28, v38, v28
	v_mul_f32_e32 v29, v39, v29
	v_cvt_pk_bf16_f32 v26, v26, v27
	v_cvt_pk_bf16_f32 v27, v28, v29
	v_mov_b32_e32 v28, v110
	v_mov_b32_e32 v29, v111
	v_mov_b32_e32 v30, v112
	v_mov_b32_e32 v31, v113
	v_mul_f32_e32 v32, v88, v40
	s_add_u32 s6, s6, s2
	v_lshlrev_b32_e32 v36, 11, v162
	v_mov_b32_e32 v37, v17
	s_addc_u32 s7, s7, 0
	v_lshlrev_b32_e32 v38, 1, v164
	v_mov_b32_e32 v39, v17
	v_lshl_add_u64 v[36:37], s[6:7], 0, v[36:37]
	v_lshl_add_u64 v[36:37], v[36:37], 0, v[38:39]
	v_add_co_u32_e32 v38, vcc, s10, v36
	v_mul_f32_e32 v41, v74, v40
	s_nop 0
	v_addc_co_u32_e32 v39, vcc, 0, v37, vcc
	v_mul_f32_e32 v42, v75, v40
	v_mul_f32_e32 v43, v76, v40
	v_mul_f32_e32 v44, v77, v40
	s_mov_b64 s[6:7], 0x3100500
	v_lshl_add_u64 v[36:37], v[36:37], 0, s[6:7]
	v_mul_f32_e32 v34, v34, v40
	v_mul_f32_e32 v35, v35, v40
	v_mul_f32_e32 v22, v22, v40
	v_mul_f32_e32 v23, v23, v40
	v_mul_f32_e32 v24, v24, v40
	v_mul_f32_e32 v25, v25, v40
	s_nop 1
	v_mul_f32_e32 v28, v28, v32
	v_mul_f32_e32 v32, v89, v40
	v_mul_f32_e32 v29, v29, v32
	v_mul_f32_e32 v32, v90, v40
	v_mul_f32_e32 v30, v30, v32
	v_mul_f32_e32 v32, v91, v40
	v_mul_f32_e32 v31, v31, v32
	v_cvt_pk_bf16_f32 v28, v28, v29
	v_cvt_pk_bf16_f32 v29, v30, v31
	v_mov_b32_e32 v30, v114
	v_mov_b32_e32 v31, v115
	v_mov_b32_e32 v32, v116
	v_mov_b32_e32 v33, v117
	v_permlane32_swap_b32_e32 v26, v28
	v_permlane32_swap_b32_e32 v27, v29
	global_store_dwordx4 v[38:39], v[26:29], off offset:1280
	v_mul_f32_e32 v38, v80, v40
	v_mul_f32_e32 v39, v81, v40
	s_nop 1
	v_mul_f32_e32 v26, v41, v30
	v_mul_f32_e32 v27, v42, v31
	v_mul_f32_e32 v28, v43, v32
	v_mul_f32_e32 v29, v44, v33
	v_cvt_pk_bf16_f32 v26, v26, v27
	v_cvt_pk_bf16_f32 v27, v28, v29
	v_mov_b32_e32 v28, v118
	v_mov_b32_e32 v29, v119
	v_mov_b32_e32 v30, v120
	v_mov_b32_e32 v31, v121
	v_mul_f32_e32 v32, v78, v40
	v_mul_f32_e32 v33, v79, v40
	v_mul_f32_e32 v41, v68, v40
	v_mul_f32_e32 v42, v69, v40
	s_nop 1
	v_mul_f32_e32 v28, v32, v28
	v_mul_f32_e32 v29, v33, v29
	v_mul_f32_e32 v30, v38, v30
	v_mul_f32_e32 v31, v39, v31
	v_cvt_pk_bf16_f32 v28, v28, v29
	v_cvt_pk_bf16_f32 v29, v30, v31
	v_mov_b32_e32 v30, v122
	v_mov_b32_e32 v31, v123
	v_mov_b32_e32 v32, v124
	v_mov_b32_e32 v33, v125
	v_mul_f32_e32 v38, v66, v40
	v_mul_f32_e32 v39, v67, v40
	v_permlane32_swap_b32_e32 v26, v28
; __device__ __forceinline__ u32x2 pack4(float a, float b, float c, float d) { u32x2 r = {cvtpk(a, b), cvtpk(c, d)}; return r; }
; template <int MODE> __device__ __forceinline__ void diff_attn_item(const bf16* __restrict__ Qb, const bf16* __restrict__ Kh, const bf16* __restrict__ Vh, ...
;     ...
; #pragma unroll
;     for (int d0 = 0; d0 < 4; ++d0)
; #pragma unroll
;       for (int ip = 0; ip < 2; ++ip) {
;         u32x2 pk[2];
; #pragma unroll
;         for (int e = 0; e < 2; ++e) {
;           const int i = ip * 2 + e, dim = d0 * 32 + i * 8;
;           float4 g4 = *reinterpret_cast<const float4*>(sub_g + dim + hi * 4);
;           pk[e] = pack4(o[d0][4 * i] * rstd * g4.x, o[d0][4 * i + 1] * rstd * g4.y, o[d0][4 * i + 2] * rstd * g4.z, o[d0][4 * i + 3] * rstd * g4.w);
;         }
;         *reinterpret_cast<u32x4*>(orow + d0 * 32 + (ip * 2 + hi) * 8) = widen_pair(pk[0], pk[1]);
;       }
	v_permlane32_swap_b32_e32 v27, v29
	global_store_dwordx4 v[36:37], v[26:29], off offset:32
	s_nop 1
	s_nop 0
	v_mul_f32_e32 v26, v38, v30
	v_mul_f32_e32 v27, v39, v31
	v_mul_f32_e32 v28, v41, v32
	v_mul_f32_e32 v29, v42, v33
	v_cvt_pk_bf16_f32 v26, v26, v27
	v_cvt_pk_bf16_f32 v27, v28, v29
	v_mov_b32_e32 v28, v126
	v_mov_b32_e32 v29, v127
	v_mov_b32_e32 v30, v128
	v_mov_b32_e32 v31, v129
	v_mul_f32_e32 v32, v70, v40
	v_mul_f32_e32 v33, v71, v40
	v_mul_f32_e32 v38, v72, v40
	v_mul_f32_e32 v39, v73, v40
	v_mul_f32_e32 v41, v60, v40
	v_mul_f32_e32 v42, v61, v40
	s_nop 1
	v_mul_f32_e32 v28, v32, v28
	v_mul_f32_e32 v29, v33, v29
	v_mul_f32_e32 v30, v38, v30
	v_mul_f32_e32 v31, v39, v31
	v_cvt_pk_bf16_f32 v28, v28, v29
	v_cvt_pk_bf16_f32 v29, v30, v31
	v_mov_b32_e32 v30, v130
	v_mov_b32_e32 v31, v131
	v_mov_b32_e32 v32, v132
	v_mov_b32_e32 v33, v133
	v_mul_f32_e32 v38, v58, v40
	v_mul_f32_e32 v39, v59, v40
	v_permlane32_swap_b32_e32 v26, v28
	v_permlane32_swap_b32_e32 v27, v29
	global_store_dwordx4 v[36:37], v[26:29], off offset:64
	s_nop 1
	s_nop 0
	v_mul_f32_e32 v26, v38, v30
	v_mul_f32_e32 v27, v39, v31
	v_mul_f32_e32 v28, v41, v32
	v_mul_f32_e32 v29, v42, v33
	v_cvt_pk_bf16_f32 v26, v26, v27
	v_cvt_pk_bf16_f32 v27, v28, v29
	v_mov_b32_e32 v28, v134
	v_mov_b32_e32 v29, v135
	v_mov_b32_e32 v30, v136
	v_mov_b32_e32 v31, v137
	v_mul_f32_e32 v32, v62, v40
	v_mul_f32_e32 v33, v63, v40
	v_mul_f32_e32 v38, v64, v40
	v_mul_f32_e32 v39, v65, v40
	v_mul_f32_e32 v41, v98, v40
	v_mul_f32_e32 v42, v99, v40
	s_nop 1
	v_mul_f32_e32 v28, v32, v28
	v_mul_f32_e32 v29, v33, v29
	v_mul_f32_e32 v30, v38, v30
	v_mul_f32_e32 v31, v39, v31
	v_cvt_pk_bf16_f32 v28, v28, v29
	v_cvt_pk_bf16_f32 v29, v30, v31
	v_mov_b32_e32 v30, v138
	v_mov_b32_e32 v31, v139
	v_mov_b32_e32 v32, v140
	v_mov_b32_e32 v33, v141
	v_mul_f32_e32 v38, v96, v40
	v_mul_f32_e32 v39, v97, v40
	v_permlane32_swap_b32_e32 v26, v28
	v_permlane32_swap_b32_e32 v27, v29
	global_store_dwordx4 v[36:37], v[26:29], off offset:96
	s_nop 1
	s_nop 0
	v_mul_f32_e32 v26, v38, v30
	v_mul_f32_e32 v27, v39, v31
	v_mul_f32_e32 v28, v41, v32
	v_mul_f32_e32 v29, v42, v33
	v_cvt_pk_bf16_f32 v26, v26, v27
	v_cvt_pk_bf16_f32 v27, v28, v29
	v_mov_b32_e32 v28, v142
	v_mov_b32_e32 v29, v143
	v_mov_b32_e32 v30, v144
	v_mov_b32_e32 v31, v145
	v_mul_f32_e32 v32, v54, v40
	v_mul_f32_e32 v33, v55, v40
	v_mul_f32_e32 v38, v56, v40
	v_mul_f32_e32 v39, v57, v40
	v_mul_f32_e32 v41, v102, v40
	v_mul_f32_e32 v42, v103, v40
	s_nop 1
	v_mul_f32_e32 v28, v32, v28
	v_mul_f32_e32 v29, v33, v29
	v_mul_f32_e32 v30, v38, v30
	v_mul_f32_e32 v31, v39, v31
	v_cvt_pk_bf16_f32 v28, v28, v29
	v_cvt_pk_bf16_f32 v29, v30, v31
	v_mov_b32_e32 v30, v146
	v_mov_b32_e32 v31, v147
	v_mov_b32_e32 v32, v148
	v_mov_b32_e32 v33, v149
	v_mul_f32_e32 v38, v100, v40
	v_mul_f32_e32 v39, v101, v40
	v_permlane32_swap_b32_e32 v26, v28
	v_permlane32_swap_b32_e32 v27, v29
	global_store_dwordx4 v[36:37], v[26:29], off offset:128
	s_nop 1
	s_nop 0
	v_mul_f32_e32 v26, v38, v30
	v_mul_f32_e32 v27, v39, v31
	v_mul_f32_e32 v28, v41, v32
	v_mul_f32_e32 v29, v42, v33
	v_cvt_pk_bf16_f32 v26, v26, v27
	v_cvt_pk_bf16_f32 v27, v28, v29
	v_mov_b32_e32 v28, v150
	v_mov_b32_e32 v29, v151
	v_mov_b32_e32 v30, v152
	v_mov_b32_e32 v31, v153
	v_mul_f32_e32 v32, v46, v40
	v_mul_f32_e32 v33, v47, v40
	v_mul_f32_e32 v38, v48, v40
	v_mul_f32_e32 v39, v49, v40
	v_mul_f32_e32 v41, v52, v40
	v_mul_f32_e32 v42, v53, v40
	s_nop 1
	v_mul_f32_e32 v28, v32, v28
	v_mul_f32_e32 v29, v33, v29
	v_mul_f32_e32 v30, v38, v30
	v_mul_f32_e32 v31, v39, v31
	v_cvt_pk_bf16_f32 v28, v28, v29
	v_cvt_pk_bf16_f32 v29, v30, v31
	v_mov_b32_e32 v30, v154
	v_mov_b32_e32 v31, v155
	v_mov_b32_e32 v32, v156
	v_mov_b32_e32 v33, v157
	v_mul_f32_e32 v38, v50, v40
	v_mul_f32_e32 v39, v51, v40
	v_permlane32_swap_b32_e32 v26, v28
	v_permlane32_swap_b32_e32 v27, v29
	global_store_dwordx4 v[36:37], v[26:29], off offset:160
	s_nop 1
	s_nop 0
	v_mul_f32_e32 v26, v38, v30
	v_mul_f32_e32 v27, v39, v31
	v_mul_f32_e32 v28, v41, v32
	v_mul_f32_e32 v29, v42, v33
	v_cvt_pk_bf16_f32 v26, v26, v27
	v_cvt_pk_bf16_f32 v27, v28, v29
	v_mov_b32_e32 v28, v158
	v_mov_b32_e32 v29, v159
	v_mov_b32_e32 v30, v160
	v_mov_b32_e32 v31, v161
	v_mul_f32_e32 v32, v104, v40
	v_mul_f32_e32 v33, v105, v40
	s_nop 1
	v_mul_f32_e32 v28, v32, v28
	v_mul_f32_e32 v29, v33, v29
	v_mul_f32_e32 v30, v34, v30
	v_mul_f32_e32 v31, v35, v31
	v_cvt_pk_bf16_f32 v28, v28, v29
	v_cvt_pk_bf16_f32 v29, v30, v31
	v_mov_b32_e32 v30, v200
	v_mov_b32_e32 v31, v201
	v_mov_b32_e32 v32, v202
	v_mov_b32_e32 v33, v203
	v_permlane32_swap_b32_e32 v26, v28
	v_permlane32_swap_b32_e32 v27, v29
	global_store_dwordx4 v[36:37], v[26:29], off offset:192
	s_nop 1
	v_mul_f32_e32 v22, v22, v30
	v_mul_f32_e32 v23, v23, v31
	v_mul_f32_e32 v24, v24, v32
	v_mul_f32_e32 v25, v25, v33
	v_cvt_pk_bf16_f32 v22, v22, v23
	v_cvt_pk_bf16_f32 v23, v24, v25
	v_mov_b32_e32 v24, v204
	v_mov_b32_e32 v25, v205
	v_mov_b32_e32 v26, v206
	v_mov_b32_e32 v27, v207
	v_mul_f32_e32 v16, v18, v40
	v_mul_f32_e32 v18, v19, v40
	v_mul_f32_e32 v19, v20, v40
	v_mul_f32_e32 v20, v21, v40
	s_nop 1
	v_mul_f32_e32 v16, v16, v24
	v_mul_f32_e32 v18, v18, v25
	v_mul_f32_e32 v19, v19, v26
	v_mul_f32_e32 v20, v20, v27
	v_cvt_pk_bf16_f32 v24, v16, v18
	v_cvt_pk_bf16_f32 v25, v19, v20
	s_nop 0
	v_permlane32_swap_b32_e32 v22, v24
	v_permlane32_swap_b32_e32 v23, v25
	global_store_dwordx4 v[36:37], v[22:25], off offset:224
	s_branch .LBB0_787

; template <int MODE> __device__ __forceinline__ void diff_attn_item(const bf16* __restrict__ Qb, const bf16* __restrict__ Kh, const bf16* __restrict__ Vh, ...
;     ...
;   if (map == 0) {
;     float ss = 0;
; #pragma unroll
;     for (int d0 = 0; d0 < 4; ++d0)
; #pragma unroll
;       for (int r = 0; r < 16; ++r) { float v = o[d0][r] * rl - E[((rb * 4 + d0) * 16 + r) * 64 + lane]; o[d0][r] = v; ss += v * v; }
;     ss += __shfl_xor(ss, 32);
;     const float rstd = rsqrtf(ss * (1.f / 128.f) + EPS) * oscale;
.LBB0_1996:
	s_or_b64 exec, exec, s[8:9]
	s_movk_i32 s4, 0x100
	v_cmp_gt_u32_e32 vcc, s4, v163
	s_waitcnt lgkmcnt(0)
	s_barrier
	s_and_saveexec_b64 s[8:9], vcc
	s_cbranch_execz .LBB0_1871
	global_load_dwordx4 v[106:109], v16, s[6:7] offset:512
	global_load_dwordx4 v[110:113], v16, s[6:7] offset:544
	global_load_dwordx4 v[114:117], v16, s[6:7] offset:576
	global_load_dwordx4 v[118:121], v16, s[6:7] offset:608
	global_load_dwordx4 v[122:125], v16, s[6:7] offset:640
	global_load_dwordx4 v[126:129], v16, s[6:7] offset:672
	global_load_dwordx4 v[130:133], v16, s[6:7] offset:704
	global_load_dwordx4 v[134:137], v16, s[6:7] offset:736
	global_load_dwordx4 v[138:141], v16, s[6:7] offset:768
	global_load_dwordx4 v[142:145], v16, s[6:7] offset:800
	global_load_dwordx4 v[146:149], v16, s[6:7] offset:832
	global_load_dwordx4 v[150:153], v16, s[6:7] offset:864
	global_load_dwordx4 v[154:157], v16, s[6:7] offset:896
	global_load_dwordx4 v[158:161], v16, s[6:7] offset:928
	global_load_dwordx4 v[200:203], v16, s[6:7] offset:960
	global_load_dwordx4 v[204:207], v16, s[6:7] offset:992
	v_lshlrev_b32_e32 v93, 8, v163
	v_lshl_add_u32 v92, v178, 2, 0
	v_and_b32_e32 v84, 0xc000, v93
	v_add_u32_e32 v94, v92, v84
	ds_read2st64_b32 v[84:85], v94 offset1:1
	ds_read2st64_b32 v[86:87], v94 offset0:2 offset1:3
	ds_read2st64_b32 v[88:89], v94 offset0:4 offset1:5
	ds_read2st64_b32 v[90:91], v94 offset0:6 offset1:7
	s_mov_b32 s4, 0x800000
	s_waitcnt lgkmcnt(3)
	v_fma_f32 v84, v66, v82, -v84
	v_fma_f32 v85, v67, v82, -v85
	s_waitcnt lgkmcnt(2)
	v_fma_f32 v86, v68, v82, -v86
	v_fma_f32 v87, v69, v82, -v87
	s_waitcnt lgkmcnt(1)
	v_fma_f32 v88, v70, v82, -v88
	v_fma_f32 v89, v71, v82, -v89
	s_waitcnt lgkmcnt(0)
	v_fma_f32 v90, v72, v82, -v90
	v_fma_f32 v91, v73, v82, -v91
	ds_read2st64_b32 v[66:67], v94 offset0:8 offset1:9
	ds_read2st64_b32 v[68:69], v94 offset0:10 offset1:11
	ds_read2st64_b32 v[70:71], v94 offset0:12 offset1:13
	ds_read2st64_b32 v[72:73], v94 offset0:14 offset1:15
	v_mul_f32_e32 v95, v85, v85
	v_fmac_f32_e32 v95, v84, v84
	s_waitcnt lgkmcnt(2)
	v_fma_f32 v76, v76, v82, -v68
	v_fma_f32 v74, v74, v82, -v66
	v_fma_f32 v75, v75, v82, -v67
	v_fma_f32 v77, v77, v82, -v69
	s_waitcnt lgkmcnt(1)
	v_fma_f32 v78, v78, v82, -v70
	v_fma_f32 v79, v79, v82, -v71
	s_waitcnt lgkmcnt(0)
	v_fma_f32 v80, v80, v82, -v72
	v_fma_f32 v81, v81, v82, -v73
	ds_read2st64_b32 v[66:67], v94 offset0:16 offset1:17
	ds_read2st64_b32 v[68:69], v94 offset0:18 offset1:19
	ds_read2st64_b32 v[70:71], v94 offset0:20 offset1:21
	ds_read2st64_b32 v[72:73], v94 offset0:22 offset1:23
	v_fmac_f32_e32 v95, v86, v86
	v_fmac_f32_e32 v95, v87, v87
	s_waitcnt lgkmcnt(2)
	v_fma_f32 v68, v52, v82, -v68
	v_fma_f32 v66, v50, v82, -v66
	v_fma_f32 v67, v51, v82, -v67
	v_fma_f32 v69, v53, v82, -v69
	s_waitcnt lgkmcnt(1)
	v_fma_f32 v70, v54, v82, -v70
	v_fma_f32 v71, v55, v82, -v71
	s_waitcnt lgkmcnt(0)
	v_fma_f32 v72, v56, v82, -v72
	v_fma_f32 v73, v57, v82, -v73
	ds_read2st64_b32 v[50:51], v94 offset0:24 offset1:25
	ds_read2st64_b32 v[52:53], v94 offset0:26 offset1:27
	ds_read2st64_b32 v[54:55], v94 offset0:28 offset1:29
	ds_read2st64_b32 v[56:57], v94 offset0:30 offset1:31
	v_fmac_f32_e32 v95, v88, v88
	v_fmac_f32_e32 v95, v89, v89
	s_waitcnt lgkmcnt(2)
	v_fma_f32 v60, v60, v82, -v52
	v_fma_f32 v58, v58, v82, -v50
	v_fma_f32 v59, v59, v82, -v51
	v_fma_f32 v61, v61, v82, -v53
	s_waitcnt lgkmcnt(1)
	v_fma_f32 v62, v62, v82, -v54
	v_fma_f32 v63, v63, v82, -v55
	s_waitcnt lgkmcnt(0)
	v_fma_f32 v64, v64, v82, -v56
	v_fma_f32 v65, v65, v82, -v57
	ds_read2st64_b32 v[50:51], v94 offset0:32 offset1:33
	ds_read2st64_b32 v[52:53], v94 offset0:34 offset1:35
	ds_read2st64_b32 v[54:55], v94 offset0:36 offset1:37
	ds_read2st64_b32 v[56:57], v94 offset0:38 offset1:39
	v_fmac_f32_e32 v95, v90, v90
	v_fmac_f32_e32 v95, v91, v91
	v_fmac_f32_e32 v95, v74, v74
	v_fmac_f32_e32 v95, v75, v75
	s_waitcnt lgkmcnt(2)
	v_fma_f32 v98, v36, v82, -v52
	v_fma_f32 v99, v37, v82, -v53
	s_waitcnt lgkmcnt(1)
	v_fma_f32 v54, v38, v82, -v54
	v_fma_f32 v55, v39, v82, -v55
	v_fmac_f32_e32 v95, v76, v76
	v_fmac_f32_e32 v95, v77, v77
	v_fmac_f32_e32 v95, v78, v78
	v_fmac_f32_e32 v95, v79, v79
	v_fmac_f32_e32 v95, v80, v80
	v_fmac_f32_e32 v95, v81, v81
	v_fmac_f32_e32 v95, v66, v66
	v_fmac_f32_e32 v95, v67, v67
	v_fmac_f32_e32 v95, v68, v68
	v_fmac_f32_e32 v95, v69, v69
	v_fmac_f32_e32 v95, v70, v70
	v_fmac_f32_e32 v95, v71, v71
	v_fmac_f32_e32 v95, v72, v72
	v_fmac_f32_e32 v95, v73, v73
	v_fmac_f32_e32 v95, v58, v58
	v_fmac_f32_e32 v95, v59, v59
	v_fmac_f32_e32 v95, v60, v60
	v_fmac_f32_e32 v95, v61, v61
	v_fmac_f32_e32 v95, v62, v62
	v_fmac_f32_e32 v95, v63, v63
	v_fmac_f32_e32 v95, v64, v64
	v_fmac_f32_e32 v95, v65, v65
	v_fma_f32 v96, v34, v82, -v50
	v_fmac_f32_e32 v95, v96, v96
	v_fma_f32 v97, v35, v82, -v51
	v_fmac_f32_e32 v95, v97, v97
	v_fmac_f32_e32 v95, v98, v98
	ds_read2st64_b32 v[34:35], v94 offset0:40 offset1:41
	v_fmac_f32_e32 v95, v99, v99
	v_fmac_f32_e32 v95, v54, v54
	v_fmac_f32_e32 v95, v55, v55
	s_waitcnt lgkmcnt(1)
	v_fma_f32 v56, v40, v82, -v56
	v_fmac_f32_e32 v95, v56, v56
	v_fma_f32 v57, v41, v82, -v57
	ds_read2st64_b32 v[40:41], v94 offset0:42 offset1:43
	ds_read2st64_b32 v[50:51], v94 offset0:44 offset1:45
	ds_read2st64_b32 v[52:53], v94 offset0:46 offset1:47
	v_fmac_f32_e32 v95, v57, v57
	s_waitcnt lgkmcnt(3)
	v_fma_f32 v100, v42, v82, -v34
	v_fmac_f32_e32 v95, v100, v100
	v_fma_f32 v101, v43, v82, -v35
	v_fmac_f32_e32 v95, v101, v101
	s_waitcnt lgkmcnt(2)
	v_fma_f32 v102, v44, v82, -v40
	v_fmac_f32_e32 v95, v102, v102
	v_fma_f32 v103, v45, v82, -v41
	ds_read2st64_b32 v[34:35], v94 offset0:48 offset1:49
	v_fmac_f32_e32 v95, v103, v103
	s_waitcnt lgkmcnt(2)
; __device__ __forceinline__ u32x2 pack4(float a, float b, float c, float d) { u32x2 r = {cvtpk(a, b), cvtpk(c, d)}; return r; }
; template <int MODE> __device__ __forceinline__ void diff_attn_item(const bf16* __restrict__ Qb, const bf16* __restrict__ Kh, const bf16* __restrict__ Vh, ...
;     ...
;       for (int r = 0; r < 16; ++r) { float v = o[d0][r] * rl - E[((rb * 4 + d0) * 16 + r) * 64 + lane]; o[d0][r] = v; ss += v * v; }
;     ss += __shfl_xor(ss, 32);
;     const float rstd = rsqrtf(ss * (1.f / 128.f) + EPS) * oscale;
;     bf16* orow = outb + (size_t)(rb * 32 + r32) * 1024;
; #pragma unroll
;     for (int d0 = 0; d0 < 4; ++d0)
; #pragma unroll
;       for (int ip = 0; ip < 2; ++ip) {
;         u32x2 pk[2];
; #pragma unroll
;         for (int e = 0; e < 2; ++e) {
;           const int i = ip * 2 + e, dim = d0 * 32 + i * 8;
;           float4 g4 = *reinterpret_cast<const float4*>(sub_g + dim + hi * 4);
;           pk[e] = pack4(o[d0][4 * i] * rstd * g4.x, o[d0][4 * i + 1] * rstd * g4.y, o[d0][4 * i + 2] * rstd * g4.z, o[d0][4 * i + 3] * rstd * g4.w);
;         }
;         *reinterpret_cast<u32x4*>(orow + d0 * 32 + (ip * 2 + hi) * 8) = widen_pair(pk[0], pk[1]);
	v_fma_f32 v46, v46, v82, -v50
	v_fmac_f32_e32 v95, v46, v46
	v_fma_f32 v47, v47, v82, -v51
	v_fmac_f32_e32 v95, v47, v47
	s_waitcnt lgkmcnt(1)
	v_fma_f32 v48, v48, v82, -v52
	v_fmac_f32_e32 v95, v48, v48
	v_fma_f32 v49, v49, v82, -v53
	ds_read2st64_b32 v[40:41], v94 offset0:50 offset1:51
	ds_read2st64_b32 v[42:43], v94 offset0:52 offset1:53
	ds_read2st64_b32 v[44:45], v94 offset0:54 offset1:55
	v_fmac_f32_e32 v95, v49, v49
	s_waitcnt lgkmcnt(3)
	v_fma_f32 v50, v18, v82, -v34
	v_fmac_f32_e32 v95, v50, v50
	v_fma_f32 v51, v19, v82, -v35
	v_fmac_f32_e32 v95, v51, v51
	s_waitcnt lgkmcnt(2)
	v_fma_f32 v52, v20, v82, -v40
	v_fmac_f32_e32 v95, v52, v52
	v_fma_f32 v53, v21, v82, -v41
	v_fmac_f32_e32 v95, v53, v53
	s_waitcnt lgkmcnt(1)
	v_fma_f32 v104, v22, v82, -v42
	ds_read2st64_b32 v[20:21], v94 offset0:56 offset1:57
	v_fmac_f32_e32 v95, v104, v104
	v_fma_f32 v105, v23, v82, -v43
	s_waitcnt lgkmcnt(1)
	v_pk_fma_f32 v[34:35], v[24:25], v[82:83], v[44:45] op_sel_hi:[1,0,1] neg_lo:[0,0,1] neg_hi:[0,0,1]
	v_fmac_f32_e32 v95, v105, v105
	v_pk_mul_f32 v[18:19], v[34:35], v[34:35]
	s_waitcnt lgkmcnt(0)
	v_pk_fma_f32 v[22:23], v[26:27], v[82:83], v[20:21] op_sel_hi:[1,0,1] neg_lo:[0,0,1] neg_hi:[0,0,1]
	v_add_f32_e32 v18, v95, v18
	v_add_f32_e32 v24, v18, v19
	ds_read2st64_b32 v[18:19], v94 offset0:58 offset1:59
	ds_read2st64_b32 v[40:41], v94 offset0:60 offset1:61
	ds_read_b32 v42, v94 offset:15872
	v_pk_mul_f32 v[20:21], v[22:23], v[22:23]
	s_lshl_b32 s5, s13, 13
	v_add_f32_e32 v20, v24, v20
	s_waitcnt lgkmcnt(2)
	v_pk_fma_f32 v[24:25], v[28:29], v[82:83], v[18:19] op_sel_hi:[1,0,1] neg_lo:[0,0,1] neg_hi:[0,0,1]
	v_add_f32_e32 v20, v20, v21
	v_pk_mul_f32 v[18:19], v[24:25], v[24:25]
	s_mov_b32 s10, 0x3100000
	v_add_f32_e32 v18, v20, v18
	v_add_f32_e32 v26, v18, v19
	v_or_b32_e32 v18, 0x3f00, v93
	v_add_u32_e32 v18, v92, v18
	ds_read_b32 v43, v18
	s_waitcnt lgkmcnt(2)
	v_pk_fma_f32 v[18:19], v[30:31], v[82:83], v[40:41] op_sel_hi:[1,0,1] neg_lo:[0,0,1] neg_hi:[0,0,1]
	s_nop 0
	v_pk_mul_f32 v[20:21], v[18:19], v[18:19]
	s_nop 0
	v_add_f32_e32 v20, v26, v20
	v_add_f32_e32 v28, v20, v21
	s_waitcnt lgkmcnt(0)
	v_pk_fma_f32 v[20:21], v[32:33], v[82:83], v[42:43] op_sel_hi:[1,0,1] neg_lo:[0,0,1] neg_hi:[0,0,1]
	s_nop 0
	v_pk_mul_f32 v[26:27], v[20:21], v[20:21]
	s_nop 0
	v_add_f32_e32 v26, v28, v26
	v_add_f32_e32 v26, v26, v27
	ds_bpermute_b32 v27, v83, v26
	s_waitcnt lgkmcnt(0)
	v_add_f32_e32 v26, v26, v27
	v_fmamk_f32 v26, v26, 0x3c000000, v175
	v_mul_f32_e32 v27, 0x4b800000, v26
	v_cmp_gt_f32_e32 vcc, s4, v26
	s_lshl_b32 s4, s12, 7
	s_or_b32 s4, s5, s4
	v_cndmask_b32_e32 v26, v26, v27, vcc
	v_rsq_f32_e32 v26, v26
	s_ashr_i32 s5, s4, 31
	s_lshl_b64 s[4:5], s[4:5], 11
	v_mul_f32_e32 v27, 0x45800000, v26
	v_cndmask_b32_e32 v26, v26, v27, vcc
	v_mul_f32_e32 v40, 0x3f24fd5c, v26
	v_mul_f32_e32 v26, v84, v40
	v_mul_f32_e32 v27, v85, v40
	v_mul_f32_e32 v28, v86, v40
	v_mul_f32_e32 v29, v87, v40
	s_waitcnt vmcnt(0)
	v_mov_b32_e32 v36, v106
	v_mov_b32_e32 v37, v107
	v_mov_b32_e32 v38, v108
	v_mov_b32_e32 v39, v109
	v_mul_f32_e32 v26, v36, v26
	v_mul_f32_e32 v27, v37, v27
	v_mul_f32_e32 v28, v38, v28
	v_mul_f32_e32 v29, v39, v29
	v_cvt_pk_bf16_f32 v26, v26, v27
	v_cvt_pk_bf16_f32 v27, v28, v29
	v_mov_b32_e32 v28, v110
	v_mov_b32_e32 v29, v111
	v_mov_b32_e32 v30, v112
	v_mov_b32_e32 v31, v113
	v_mul_f32_e32 v32, v88, v40
	v_lshlrev_b32_e32 v36, 11, v162
	v_mov_b32_e32 v37, v17
	v_lshlrev_b32_e32 v38, 1, v164
	v_mov_b32_e32 v39, v17
	v_mul_f32_e32 v41, v74, v40
	v_mul_f32_e32 v42, v75, v40
	v_mul_f32_e32 v43, v76, v40
	v_mul_f32_e32 v44, v77, v40
	v_mul_f32_e32 v34, v34, v40
	v_mul_f32_e32 v35, v35, v40
	v_mul_f32_e32 v22, v22, v40
	v_mul_f32_e32 v23, v23, v40
	v_mul_f32_e32 v24, v24, v40
	v_mul_f32_e32 v25, v25, v40
	s_nop 1
	v_mul_f32_e32 v28, v28, v32
	v_mul_f32_e32 v32, v89, v40
	v_mul_f32_e32 v29, v29, v32
	v_mul_f32_e32 v32, v90, v40
	v_mul_f32_e32 v30, v30, v32
	v_mul_f32_e32 v32, v91, v40
	v_mul_f32_e32 v31, v31, v32
	v_cvt_pk_bf16_f32 v28, v28, v29
	v_cvt_pk_bf16_f32 v29, v30, v31
	v_mov_b32_e32 v30, v114
	v_mov_b32_e32 v31, v115
	v_mov_b32_e32 v32, v116
	v_mov_b32_e32 v33, v117
	s_load_dwordx2 s[12:13], s[0:1], 0xd8
	v_permlane32_swap_b32_e32 v26, v28
	v_permlane32_swap_b32_e32 v27, v29
	s_waitcnt lgkmcnt(0)
; __device__ __forceinline__ u32x2 pack4(float a, float b, float c, float d) { u32x2 r = {cvtpk(a, b), cvtpk(c, d)}; return r; }
; template <int MODE> __device__ __forceinline__ void diff_attn_item(const bf16* __restrict__ Qb, const bf16* __restrict__ Kh, const bf16* __restrict__ Vh, ...
;     ...
; #pragma unroll
;     for (int d0 = 0; d0 < 4; ++d0)
; #pragma unroll
;       for (int ip = 0; ip < 2; ++ip) {
;         u32x2 pk[2];
; #pragma unroll
;         for (int e = 0; e < 2; ++e) {
;           const int i = ip * 2 + e, dim = d0 * 32 + i * 8;
;           float4 g4 = *reinterpret_cast<const float4*>(sub_g + dim + hi * 4);
;           pk[e] = pack4(o[d0][4 * i] * rstd * g4.x, o[d0][4 * i + 1] * rstd * g4.y, o[d0][4 * i + 2] * rstd * g4.z, o[d0][4 * i + 3] * rstd * g4.w);
;         }
;         *reinterpret_cast<u32x4*>(orow + d0 * 32 + (ip * 2 + hi) * 8) = widen_pair(pk[0], pk[1]);
;       }
	s_add_u32 s4, s12, s4
	s_addc_u32 s5, s13, s5
	s_lshl_b32 s3, s3, 8
	s_add_u32 s4, s4, s3
	s_addc_u32 s5, s5, 0
	v_lshl_add_u64 v[36:37], s[4:5], 0, v[36:37]
	v_lshl_add_u64 v[36:37], v[36:37], 0, v[38:39]
	v_add_co_u32_e32 v38, vcc, s10, v36
	s_mov_b64 s[4:5], 0x3100500
	s_nop 0
	v_addc_co_u32_e32 v39, vcc, 0, v37, vcc
	global_store_dwordx4 v[38:39], v[26:29], off offset:1280
	v_mul_f32_e32 v38, v80, v40
	v_mul_f32_e32 v39, v81, v40
	v_lshl_add_u64 v[36:37], v[36:37], 0, s[4:5]
	s_nop 1
	v_mul_f32_e32 v26, v41, v30
	v_mul_f32_e32 v27, v42, v31
	v_mul_f32_e32 v28, v43, v32
	v_mul_f32_e32 v29, v44, v33
	v_cvt_pk_bf16_f32 v26, v26, v27
	v_cvt_pk_bf16_f32 v27, v28, v29
	v_mov_b32_e32 v28, v118
	v_mov_b32_e32 v29, v119
	v_mov_b32_e32 v30, v120
	v_mov_b32_e32 v31, v121
	v_mul_f32_e32 v32, v78, v40
	v_mul_f32_e32 v33, v79, v40
	v_mul_f32_e32 v41, v68, v40
	v_mul_f32_e32 v42, v69, v40
	s_nop 1
	v_mul_f32_e32 v28, v32, v28
	v_mul_f32_e32 v29, v33, v29
	v_mul_f32_e32 v30, v38, v30
	v_mul_f32_e32 v31, v39, v31
	v_cvt_pk_bf16_f32 v28, v28, v29
	v_cvt_pk_bf16_f32 v29, v30, v31
	v_mov_b32_e32 v30, v122
	v_mov_b32_e32 v31, v123
	v_mov_b32_e32 v32, v124
	v_mov_b32_e32 v33, v125
	v_mul_f32_e32 v38, v66, v40
	v_mul_f32_e32 v39, v67, v40
	v_permlane32_swap_b32_e32 v26, v28
	v_permlane32_swap_b32_e32 v27, v29
	global_store_dwordx4 v[36:37], v[26:29], off offset:32
	s_nop 1
	s_nop 0
	v_mul_f32_e32 v26, v38, v30
	v_mul_f32_e32 v27, v39, v31
	v_mul_f32_e32 v28, v41, v32
	v_mul_f32_e32 v29, v42, v33
	v_cvt_pk_bf16_f32 v26, v26, v27
	v_cvt_pk_bf16_f32 v27, v28, v29
	v_mov_b32_e32 v28, v126
	v_mov_b32_e32 v29, v127
	v_mov_b32_e32 v30, v128
	v_mov_b32_e32 v31, v129
	v_mul_f32_e32 v32, v70, v40
	v_mul_f32_e32 v33, v71, v40
	v_mul_f32_e32 v38, v72, v40
	v_mul_f32_e32 v39, v73, v40
	v_mul_f32_e32 v41, v60, v40
	v_mul_f32_e32 v42, v61, v40
	s_nop 1
	v_mul_f32_e32 v28, v32, v28
	v_mul_f32_e32 v29, v33, v29
	v_mul_f32_e32 v30, v38, v30
	v_mul_f32_e32 v31, v39, v31
	v_cvt_pk_bf16_f32 v28, v28, v29
	v_cvt_pk_bf16_f32 v29, v30, v31
	v_mov_b32_e32 v30, v130
	v_mov_b32_e32 v31, v131
	v_mov_b32_e32 v32, v132
	v_mov_b32_e32 v33, v133
	v_mul_f32_e32 v38, v58, v40
	v_mul_f32_e32 v39, v59, v40
	v_permlane32_swap_b32_e32 v26, v28
	v_permlane32_swap_b32_e32 v27, v29
	global_store_dwordx4 v[36:37], v[26:29], off offset:64
	s_nop 1
	s_nop 0
	v_mul_f32_e32 v26, v38, v30
	v_mul_f32_e32 v27, v39, v31
	v_mul_f32_e32 v28, v41, v32
	v_mul_f32_e32 v29, v42, v33
	v_cvt_pk_bf16_f32 v26, v26, v27
	v_cvt_pk_bf16_f32 v27, v28, v29
	v_mov_b32_e32 v28, v134
	v_mov_b32_e32 v29, v135
	v_mov_b32_e32 v30, v136
	v_mov_b32_e32 v31, v137
	v_mul_f32_e32 v32, v62, v40
	v_mul_f32_e32 v33, v63, v40
	v_mul_f32_e32 v38, v64, v40
	v_mul_f32_e32 v39, v65, v40
	v_mul_f32_e32 v41, v98, v40
	v_mul_f32_e32 v42, v99, v40
	s_nop 1
	v_mul_f32_e32 v28, v32, v28
	v_mul_f32_e32 v29, v33, v29
	v_mul_f32_e32 v30, v38, v30
	v_mul_f32_e32 v31, v39, v31
	v_cvt_pk_bf16_f32 v28, v28, v29
	v_cvt_pk_bf16_f32 v29, v30, v31
	v_mov_b32_e32 v30, v138
	v_mov_b32_e32 v31, v139
	v_mov_b32_e32 v32, v140
	v_mov_b32_e32 v33, v141
	v_mul_f32_e32 v38, v96, v40
	v_mul_f32_e32 v39, v97, v40
	v_permlane32_swap_b32_e32 v26, v28
	v_permlane32_swap_b32_e32 v27, v29
	global_store_dwordx4 v[36:37], v[26:29], off offset:96
	s_nop 1
	s_nop 0
	v_mul_f32_e32 v26, v38, v30
	v_mul_f32_e32 v27, v39, v31
	v_mul_f32_e32 v28, v41, v32
	v_mul_f32_e32 v29, v42, v33
	v_cvt_pk_bf16_f32 v26, v26, v27
	v_cvt_pk_bf16_f32 v27, v28, v29
	v_mov_b32_e32 v28, v142
	v_mov_b32_e32 v29, v143
	v_mov_b32_e32 v30, v144
	v_mov_b32_e32 v31, v145
	v_mul_f32_e32 v32, v54, v40
	v_mul_f32_e32 v33, v55, v40
	v_mul_f32_e32 v38, v56, v40
	v_mul_f32_e32 v39, v57, v40
	v_mul_f32_e32 v41, v102, v40
	v_mul_f32_e32 v42, v103, v40
	s_nop 1
	v_mul_f32_e32 v28, v32, v28
	v_mul_f32_e32 v29, v33, v29
	v_mul_f32_e32 v30, v38, v30
	v_mul_f32_e32 v31, v39, v31
	v_cvt_pk_bf16_f32 v28, v28, v29
	v_cvt_pk_bf16_f32 v29, v30, v31
	v_mov_b32_e32 v30, v146
	v_mov_b32_e32 v31, v147
	v_mov_b32_e32 v32, v148
	v_mov_b32_e32 v33, v149
	v_mul_f32_e32 v38, v100, v40
	v_mul_f32_e32 v39, v101, v40
	v_permlane32_swap_b32_e32 v26, v28
	v_permlane32_swap_b32_e32 v27, v29
	global_store_dwordx4 v[36:37], v[26:29], off offset:128
	s_nop 1
	s_nop 0
	v_mul_f32_e32 v26, v38, v30
	v_mul_f32_e32 v27, v39, v31
	v_mul_f32_e32 v28, v41, v32
	v_mul_f32_e32 v29, v42, v33
	v_cvt_pk_bf16_f32 v26, v26, v27
	v_cvt_pk_bf16_f32 v27, v28, v29
	v_mov_b32_e32 v28, v150
	v_mov_b32_e32 v29, v151
	v_mov_b32_e32 v30, v152
	v_mov_b32_e32 v31, v153
	v_mul_f32_e32 v32, v46, v40
	v_mul_f32_e32 v33, v47, v40
	v_mul_f32_e32 v38, v48, v40
	v_mul_f32_e32 v39, v49, v40
	v_mul_f32_e32 v41, v52, v40
	v_mul_f32_e32 v42, v53, v40
	s_nop 1
	v_mul_f32_e32 v28, v32, v28
	v_mul_f32_e32 v29, v33, v29
	v_mul_f32_e32 v30, v38, v30
	v_mul_f32_e32 v31, v39, v31
	v_cvt_pk_bf16_f32 v28, v28, v29
	v_cvt_pk_bf16_f32 v29, v30, v31
	v_mov_b32_e32 v30, v154
	v_mov_b32_e32 v31, v155
	v_mov_b32_e32 v32, v156
	v_mov_b32_e32 v33, v157
	v_mul_f32_e32 v38, v50, v40
	v_mul_f32_e32 v39, v51, v40
	v_permlane32_swap_b32_e32 v26, v28
	v_permlane32_swap_b32_e32 v27, v29
	global_store_dwordx4 v[36:37], v[26:29], off offset:160
	s_nop 1
	s_nop 0
	v_mul_f32_e32 v26, v38, v30
	v_mul_f32_e32 v27, v39, v31
	v_mul_f32_e32 v28, v41, v32
	v_mul_f32_e32 v29, v42, v33
	v_cvt_pk_bf16_f32 v26, v26, v27
	v_cvt_pk_bf16_f32 v27, v28, v29
	v_mov_b32_e32 v28, v158
	v_mov_b32_e32 v29, v159
	v_mov_b32_e32 v30, v160
	v_mov_b32_e32 v31, v161
	v_mul_f32_e32 v32, v104, v40
	v_mul_f32_e32 v33, v105, v40
	s_nop 1
	v_mul_f32_e32 v28, v32, v28
	v_mul_f32_e32 v29, v33, v29
	v_mul_f32_e32 v30, v34, v30
	v_mul_f32_e32 v31, v35, v31
	v_cvt_pk_bf16_f32 v28, v28, v29
	v_cvt_pk_bf16_f32 v29, v30, v31
	v_mov_b32_e32 v30, v200
	v_mov_b32_e32 v31, v201
	v_mov_b32_e32 v32, v202
	v_mov_b32_e32 v33, v203
	v_permlane32_swap_b32_e32 v26, v28
	v_permlane32_swap_b32_e32 v27, v29
	global_store_dwordx4 v[36:37], v[26:29], off offset:192
	s_nop 1
	v_mul_f32_e32 v22, v22, v30
	v_mul_f32_e32 v23, v23, v31
	v_mul_f32_e32 v24, v24, v32
	v_mul_f32_e32 v25, v25, v33
	v_cvt_pk_bf16_f32 v22, v22, v23
	v_cvt_pk_bf16_f32 v23, v24, v25
	v_mov_b32_e32 v24, v204
	v_mov_b32_e32 v25, v205
	v_mov_b32_e32 v26, v206
	v_mov_b32_e32 v27, v207
	v_mul_f32_e32 v16, v18, v40
	v_mul_f32_e32 v18, v19, v40
	v_mul_f32_e32 v19, v20, v40
	v_mul_f32_e32 v20, v21, v40
	s_nop 1
	v_mul_f32_e32 v16, v16, v24
	v_mul_f32_e32 v18, v18, v25
	v_mul_f32_e32 v19, v19, v26
	v_mul_f32_e32 v20, v20, v27
	v_cvt_pk_bf16_f32 v24, v16, v18
	v_cvt_pk_bf16_f32 v25, v19, v20
	s_nop 0
	v_permlane32_swap_b32_e32 v22, v24
	v_permlane32_swap_b32_e32 v23, v25
	global_store_dwordx4 v[36:37], v[22:25], off offset:224
	s_branch .LBB0_1871
